# forgetting-attention loop role A: next global loads moved behind the MFMA block where they fill the result wait states (stores stay between PV and QK)
# speedup vs baseline: 1.0269x; 1.0033x over previous
; __device__ __forceinline__ s16x4 vtr(ldsp p) { return __builtin_bit_cast(s16x4, __builtin_amdgcn_ds_read_tr16_b64_v4i16((LAS v4i16_t*)p)); }
; #define MASK_BLOCK() do { if (kt == 0 || kt >= diag0) { \
;             _Pragma("unroll") for (int r = 0; r < 16; ++r) { const int kpp = 64 * kt + crow(r, hi); \
;                 if (kpp < 48 || kpp > q_pp) s0[r] = -INFINITY; \
;                 if (kpp + 32 < 48 || kpp + 32 > q_pp) s1[r] = -INFINITY; } } } while (0)
; #define EXPSUM_BLOCK() do { psa = 0.f; psb = 0.f; \
;             _Pragma("unroll") for (int r = 0; r < 16; ++r) { s0[r] = __builtin_amdgcn_exp2f(s0[r]); s1[r] = __builtin_amdgcn_exp2f(s1[r]); psa += s0[r]; asm("" : "+v"(psa)); psb += s1[r]; asm("" : "+v"(psb)); } } while (0)
; template <bool DIFF>
; __device__ __forceinline__ void attn_unit(const AttnP& A, int b, int h, int qi, ldsp lds) {
;     ...
;     for (int kt = kt0; kt < nt; ++kt) {
;         if (kt + 1 < nt) LOAD_TILE(kt + 1);
;         if (64 * kt <= qmax_w) {
;             ldsp Kb = lds + (kt & 1) * STAGE; ldsp Vb = Kb + 64 * KP;
;             bf16x8 kf[8]; bf16x8 ka0, ka1, qa; f32x16 s0, s1;
;     ...
;             QK_BLOCK();
;             s16x4 vlo[8], vhi[8];
; #pragma unroll
;             for (int t = 0; t < 2; ++t)
; #pragma unroll
;                 for (int j = 0; j < 4; ++j) { vlo[t * 4 + j] = vtr(Vb + trb + (16 * j) * VP + t * 64); vhi[t * 4 + j] = vtr(Vb + trb + (16 * j + 8) * VP + t * 64); }
;             __builtin_amdgcn_sched_barrier(0);
;             MASK_BLOCK();
;             bool full = (kt == kt0);
;             float psa, psb;
;             if (!full) {
;                 EXPSUM_BLOCK();
;                 if (__any(psa + psb > 1.0e18f)) { full = true; QK_BLOCK();
.Lfa_s_top:
	s_bitcmp1_b32 s99, 0
	s_cselect_b32 s74, 0x5500, 0
	s_sub_i32 s75, 0x5500, s74
	v_add_u32_e32 v169, s74, v150
	v_add_u32_e32 v0, s74, v164
	v_add_u32_e32 v168, s75, v161
	ds_read_b64_tr_b16 v[106:107], v168 offset:9216
	ds_read_b64_tr_b16 v[108:109], v168 offset:10752
	ds_read_b64_tr_b16 v[110:111], v168 offset:9280
	ds_read_b64_tr_b16 v[112:113], v168 offset:10816
	ds_read_b64_tr_b16 v[116:117], v168 offset:12288
	ds_read_b64_tr_b16 v[118:119], v168 offset:13824
	ds_read_b64_tr_b16 v[120:121], v168 offset:12352
	ds_read_b64_tr_b16 v[122:123], v168 offset:13888
	ds_read_b64_tr_b16 v[124:125], v168 offset:15360
	ds_read_b64_tr_b16 v[126:127], v168 offset:16896
	ds_read_b64_tr_b16 v[128:129], v168 offset:15424
	ds_read_b64_tr_b16 v[130:131], v168 offset:16960
	ds_read_b64_tr_b16 v[132:133], v168 offset:18432
	ds_read_b64_tr_b16 v[134:135], v168 offset:19968
	ds_read_b64_tr_b16 v[136:137], v168 offset:18496
	ds_read_b64_tr_b16 v[138:139], v168 offset:20032
	v_mov_b32_e32 v248, s97
	ds_read_b32 v248, v248
	ds_read_b128 v[170:173], v169
	ds_read_b128 v[244:247], v169 offset:4608
	s_waitcnt lgkmcnt(15)
	v_mfma_f32_32x32x16_bf16 v[18:33], v[106:109], v[66:69], v[18:33]
	ds_read_b128 v[106:109], v169 offset:32
	s_waitcnt lgkmcnt(15)
	v_mfma_f32_32x32x16_bf16 v[2:17], v[110:113], v[66:69], v[2:17]
	ds_read_b128 v[110:113], v169 offset:4640
	s_waitcnt lgkmcnt(15)
	v_mfma_f32_32x32x16_bf16 v[18:33], v[116:119], v[70:73], v[18:33]
	ds_read_b128 v[116:119], v169 offset:64
	s_waitcnt lgkmcnt(14)
	v_mfma_f32_32x32x16_bf16 v[2:17], v[120:123], v[70:73], v[2:17]
	ds_read_b128 v[120:123], v169 offset:4672
	s_waitcnt lgkmcnt(13)
	v_mfma_f32_32x32x16_bf16 v[18:33], v[124:127], v[50:53], v[18:33]
	ds_read_b128 v[124:127], v169 offset:96
	s_waitcnt lgkmcnt(12)
	v_mfma_f32_32x32x16_bf16 v[2:17], v[128:131], v[50:53], v[2:17]
	ds_read_b128 v[128:131], v169 offset:4704
	s_waitcnt lgkmcnt(11)
	v_mfma_f32_32x32x16_bf16 v[18:33], v[132:135], v[54:57], v[18:33]
	ds_read_b128 v[132:135], v0 offset:128
	s_waitcnt lgkmcnt(10)
	v_mfma_f32_32x32x16_bf16 v[2:17], v[136:139], v[54:57], v[2:17]
	ds_read_b128 v[136:139], v0 offset:4736
	s_waitcnt vmcnt(0)
	v_add_u32_e32 v115, s75, v156
	ds_write_b128 v115, v[98:101]
	s_and_saveexec_b64 s[0:1], s[44:45]
	v_xor_b32_e32 v0, 0x80000000, v155
	v_cvt_pk_bf16_f32 v0, v0, 0
	v_lshlrev_b32_e32 v249, 16, v0
	v_sub_f32_e64 v249, -v155, v249
	v_cvt_pk_bf16_f32 v162, v249, 0
	v_lshlrev_b32_e32 v162, 16, v162
	v_sub_f32_e32 v249, v249, v162
	v_cvt_pk_bf16_f32 v249, v249, 0
	v_and_or_b32 v98, v0, s83, v162
	v_and_or_b32 v99, v249, s83, 1.0
	v_mov_b32_e32 v100, v114
	v_mov_b32_e32 v101, v1
	v_add_u32_e32 v0, s75, v159
	ds_write_b128 v0, v[98:101] offset:128
	s_mov_b64 exec, s[0:1]
	v_add_u32_e32 v115, s74, v158
	ds_write_b128 v115, v[102:105] offset:9216
	s_waitcnt lgkmcnt(12)
	v_mfma_f32_32x32x16_bf16 v[66:81], v[170:173], v[90:93], v[34:49]
	s_waitcnt lgkmcnt(11)
	v_mfma_f32_32x32x16_bf16 v[50:65], v[244:247], v[90:93], v[34:49]
	v_sub_f32_e32 v249, v160, v248
	v_cvt_pk_bf16_f32 v162, v249, 0
	v_lshlrev_b32_e32 v162, 16, v162
	s_waitcnt lgkmcnt(10)
	v_mfma_f32_32x32x16_bf16 v[66:81], v[106:109], v[82:85], v[66:81]
	s_waitcnt lgkmcnt(9)
	v_mfma_f32_32x32x16_bf16 v[50:65], v[110:113], v[82:85], v[50:65]
	v_sub_f32_e32 v249, v249, v162
	v_cvt_pk_bf16_f32 v163, v249, 0
	v_and_b32_e32 v157, 0xffff, v163
	v_lshlrev_b32_e32 v163, 16, v163
	s_waitcnt lgkmcnt(8)
	v_mfma_f32_32x32x16_bf16 v[66:81], v[116:119], v[86:89], v[66:81]
	s_waitcnt lgkmcnt(7)
	v_mfma_f32_32x32x16_bf16 v[50:65], v[120:123], v[86:89], v[50:65]
	v_sub_f32_e32 v249, v249, v163
	v_cvt_pk_bf16_f32 v249, v249, 0
	v_or_b32_e32 v162, 0x3f80, v162
	v_lshl_or_b32 v249, v249, 16, v157
	v_cndmask_b32_e64 v140, 0, v114, s[46:47]
	v_cndmask_b32_e64 v142, 0, v249, s[46:47]
	v_cndmask_b32_e64 v141, 0, v162, s[46:47]
	v_mov_b32_e32 v143, v1
	s_waitcnt lgkmcnt(6)
	v_mfma_f32_32x32x16_bf16 v[66:81], v[124:127], v[94:97], v[66:81]
	s_waitcnt lgkmcnt(5)
	v_mfma_f32_32x32x16_bf16 v[50:65], v[128:131], v[94:97], v[50:65]
	s_waitcnt lgkmcnt(4)
	v_mfma_f32_32x32x16_bf16 v[66:81], v[132:135], v[140:143], v[66:81]
	s_waitcnt lgkmcnt(3)
	v_mfma_f32_32x32x16_bf16 v[50:65], v[136:139], v[140:143], v[50:65]
	global_load_dwordx4 v[102:105], v[250:251], off
	v_lshl_add_u64 v[250:251], v[250:251], 0, s[26:27]
	global_load_dwordx4 v[98:101], v[152:153], off
	v_lshl_add_u64 v[152:153], v[152:153], 0, s[26:27]
	s_and_saveexec_b64 s[0:1], s[44:45]
	global_load_dword v155, v[252:253], off
	s_mov_b64 exec, s[0:1]
	s_mov_b64 s[0:1], 0x800
	v_lshl_add_u64 v[252:253], v[252:253], 0, s[0:1]
	s_nop 1
	v_exp_f32_e32 v106, v66
	v_exp_f32_e32 v124, v50
	v_exp_f32_e32 v107, v67
	v_exp_f32_e32 v125, v51
	v_add_f32_e32 v166, 0, v106
	v_add_f32_e32 v167, 0, v124
	v_exp_f32_e32 v108, v68
	v_exp_f32_e32 v126, v52
	v_add_f32_e32 v166, v107, v166
	v_add_f32_e32 v167, v125, v167
	v_exp_f32_e32 v109, v69
	v_exp_f32_e32 v127, v53
	v_add_f32_e32 v166, v108, v166
	v_add_f32_e32 v167, v126, v167
	v_exp_f32_e32 v110, v70
	v_exp_f32_e32 v128, v54
	v_add_f32_e32 v166, v109, v166
	v_add_f32_e32 v167, v127, v167
	v_exp_f32_e32 v111, v71
	v_exp_f32_e32 v129, v55
	v_add_f32_e32 v166, v110, v166
	v_add_f32_e32 v167, v128, v167
	v_exp_f32_e32 v112, v72
	v_exp_f32_e32 v130, v56
	v_add_f32_e32 v166, v111, v166
	v_add_f32_e32 v167, v129, v167
	v_exp_f32_e32 v113, v73
	v_exp_f32_e32 v131, v57
	v_add_f32_e32 v166, v112, v166
	v_add_f32_e32 v167, v130, v167
	v_exp_f32_e32 v116, v74
	v_exp_f32_e32 v132, v58
	v_add_f32_e32 v166, v113, v166
	v_add_f32_e32 v167, v131, v167
	v_exp_f32_e32 v117, v75
	v_exp_f32_e32 v133, v59
	v_add_f32_e32 v166, v116, v166
	v_add_f32_e32 v167, v132, v167
	v_exp_f32_e32 v118, v76
	v_exp_f32_e32 v134, v60
	v_add_f32_e32 v166, v117, v166
	v_add_f32_e32 v167, v133, v167
	v_exp_f32_e32 v119, v77
	v_exp_f32_e32 v135, v61
	v_add_f32_e32 v166, v118, v166
	v_add_f32_e32 v167, v134, v167
	v_exp_f32_e32 v120, v78
	v_exp_f32_e32 v136, v62
	v_add_f32_e32 v166, v119, v166
	v_add_f32_e32 v167, v135, v167
	v_exp_f32_e32 v121, v79
	v_exp_f32_e32 v137, v63
	v_add_f32_e32 v166, v120, v166
	v_add_f32_e32 v167, v136, v167
	v_exp_f32_e32 v122, v80
	v_exp_f32_e32 v138, v64
	v_add_f32_e32 v166, v121, v166
	v_add_f32_e32 v167, v137, v167
	v_exp_f32_e32 v123, v81
	v_exp_f32_e32 v139, v65
	v_add_f32_e32 v166, v122, v166
	v_add_f32_e32 v167, v138, v167
	s_nop 0
	v_add_f32_e32 v166, v123, v166
	v_add_f32_e32 v167, v139, v167
	v_add_f32_e32 v141, v166, v167
	v_cmp_lt_f32_e32 vcc, s85, v141
	s_cbranch_vccnz .Lfa_s_slow
; __device__ __forceinline__ s16x4 vtr(ldsp p) { return __builtin_bit_cast(s16x4, __builtin_amdgcn_ds_read_tr16_b64_v4i16((LAS v4i16_t*)p)); }
; template <bool DIFF>
; __device__ __forceinline__ void attn_unit(const AttnP& A, int b, int h, int qi, ldsp lds) {
;     ...
;             l_run += psa + psb;
;     ...
;             bf16x8 pw[4];
; #pragma unroll
;             for (int j = 0; j < 4; ++j) {
;                 u32x4 pk;
;                 if (j < 2) { const int rb = 8 * (j & 1); pk.x = cvtpk(s0[rb], s0[rb + 1]); pk.y = cvtpk(s0[rb + 2], s0[rb + 3]); pk.z = cvtpk(s0[rb + 4], s0[rb + 5]); pk.w = cvtpk(s0[rb + 6], s0[rb + 7]); }
;                 else { const int rb = 8 * (j & 1); pk.x = cvtpk(s1[rb], s1[rb + 1]); pk.y = cvtpk(s1[rb + 2], s1[rb + 3]); pk.z = cvtpk(s1[rb + 4], s1[rb + 5]); pk.w = cvtpk(s1[rb + 6], s1[rb + 7]); }
;                 pw[j] = __builtin_bit_cast(bf16x8, pk);
;             }
;             __builtin_amdgcn_sched_barrier(0);
;             __builtin_amdgcn_s_setprio(1);
; #pragma unroll
;             for (int t = 0; t < 2; ++t)
; #pragma unroll
;                 for (int j = 0; j < 4; ++j) {
;                     const bf16x8 vf = (bf16x8){vlo[t * 4 + j][0], vlo[t * 4 + j][1], vlo[t * 4 + j][2], vlo[t * 4 + j][3], vhi[t * 4 + j][0], vhi[t * 4 + j][1], vhi[t * 4 + j][2], vhi[t * 4 + j][3]};
;                     o[t] = __builtin_amdgcn_mfma_f32_32x32x16_bf16(vf, pw[j], o[t], 0, 0, 0);
;                 }
;             if (DIFF) {
; #pragma unroll
;                 for (int t = 2; t < NTD; ++t)
; #pragma unroll
;                     for (int j = 0; j < 4; ++j) { vlo[(t - 2) * 4 + j] = vtr(Vb + trb + (16 * j) * VP + t * 64); vhi[(t - 2) * 4 + j] = vtr(Vb + trb + (16 * j + 8) * VP + t * 64); }
;                 __builtin_amdgcn_sched_barrier(0);
; #pragma unroll
;                 for (int t = 2; t < NTD; ++t)
; #pragma unroll
;                     for (int j = 0; j < 4; ++j) {
;                         const int i = (t - 2) * 4 + j;
;                         const bf16x8 vf = (bf16x8){vlo[i][0], vlo[i][1], vlo[i][2], vlo[i][3], vhi[i][0], vhi[i][1], vhi[i][2], vhi[i][3]};
;                         o[t] = __builtin_amdgcn_mfma_f32_32x32x16_bf16(vf, pw[j], o[t], 0, 0, 0);
;                     }
;             }
;             __builtin_amdgcn_s_setprio(0);
;         }
;         if (kt + 1 < nt) STORE_TILE((kt + 1) & 1);
;         __syncthreads();
;     }
	v_cvt_pk_bf16_f32 v66, v106, v107
	v_cvt_pk_bf16_f32 v67, v108, v109
	v_cvt_pk_bf16_f32 v68, v110, v111
	v_cvt_pk_bf16_f32 v69, v112, v113
	v_cvt_pk_bf16_f32 v70, v116, v117
	v_cvt_pk_bf16_f32 v71, v118, v119
	v_cvt_pk_bf16_f32 v72, v120, v121
	v_cvt_pk_bf16_f32 v73, v122, v123
	v_cvt_pk_bf16_f32 v50, v124, v125
	v_cvt_pk_bf16_f32 v51, v126, v127
	v_cvt_pk_bf16_f32 v52, v128, v129
	v_cvt_pk_bf16_f32 v53, v130, v131
	v_cvt_pk_bf16_f32 v54, v132, v133
	v_cvt_pk_bf16_f32 v55, v134, v135
	v_cvt_pk_bf16_f32 v56, v136, v137
	v_cvt_pk_bf16_f32 v57, v138, v139
	v_add_f32_e32 v154, v141, v154
	s_waitcnt lgkmcnt(0)
	s_barrier
	s_add_i32 s99, s99, 1
	s_add_i32 s94, s94, 1
	s_add_i32 s97, s97, 4
	s_add_i32 s98, s98, 64
	s_add_i32 s0, s95, -1
	s_cmp_le_i32 s99, s0
	s_cbranch_scc1 .Lfa_s_top
